# skip the initial cooperative-groups grid.sync (census-based XCD barrier does not need it)
# baseline (speedup 1.0000x reference)
.LBB0_5:
	s_or_b64 exec, exec, s[4:5]
	v_readlane_b32 s4, v250, 2
	v_readlane_b32 s5, v250, 3
	s_load_dword s2, s[4:5], 0xb8
	s_waitcnt lgkmcnt(0)
	v_writelane_b32 v250, s2, 6
	s_cmp_lt_i32 s2, 2
	s_branch .LBB0_17
	v_lshrrev_b32_e32 v1, 20, v0
	v_lshrrev_b32_e32 v0, 10, v0
	v_or_b32_e32 v0, v0, v1
	s_movk_i32 s2, 0x3ff
	v_and_or_b32 v0, v0, s2, v222
	v_cmp_eq_u32_e32 vcc, 0, v0
	s_barrier
	s_and_saveexec_b64 s[4:5], vcc
	s_cbranch_execz .LBB0_16
	buffer_wbl2 sc1
	s_waitcnt vmcnt(0)
	s_load_dwordx2 s[6:7], s[6:7], 0x58
	v_mov_b32_e32 v2, 0
	s_mov_b64 s[8:9], exec
	v_mbcnt_lo_u32_b32 v1, s8, 0
	v_mbcnt_hi_u32_b32 v1, s9, v1
	s_waitcnt lgkmcnt(0)
	global_load_dword v0, v2, s[6:7] offset:40
	v_cmp_eq_u32_e32 vcc, 0, v1
	s_and_saveexec_b64 s[10:11], vcc
	s_cbranch_execz .LBB0_9
	s_bcnt1_i32_b64 s2, s[8:9]
	v_mov_b32_e32 v3, s2
	global_atomic_add v3, v2, v3, s[6:7] offset:32 sc0
